# mixer queue order: weight copies, FoX 15-5, pool, FoX 4-0, stick-breaking units last (one per workgroup at the tail)
# speedup vs baseline: 1.0121x; 1.0121x over previous
.LBB0_36:
	s_or_b64 exec, exec, s[10:11]
	s_mov_b64 s[10:11], src_shared_base
	s_xor_b64 s[40:41], s[66:67], -1
	s_xor_b64 s[44:45], s[20:21], -1
	s_add_i32 s10, 0, 0x20200
	s_cmp_lg_u32 s10, -1
	s_cselect_b32 s10, s10, 0
	s_cselect_b32 s11, s11, 0
	v_mov_b32_e32 v2, s10
	s_waitcnt lgkmcnt(0)
	v_mov_b32_e32 v3, s11
	s_waitcnt lgkmcnt(0)
	s_barrier
	flat_load_dword v0, v[2:3] sc0 sc1
	s_waitcnt vmcnt(0)
	s_mov_b64 s[38:39], -1
	s_waitcnt lgkmcnt(0)
	v_cmp_gt_i32_e32 vcc, s69, v0
	s_and_saveexec_b64 s[10:11], vcc
	s_cbranch_execz .LBB0_31
	s_cmpk_eq_i32 s69, 0x340
	s_cselect_b32 s18, 0x48, 0
	v_cmp_le_u32_e32 vcc, 0, v0
	v_mov_b32_e32 v2, s18
	s_nop 0
	v_cndmask_b32_e32 v2, 0, v2, vcc
	v_add_u32_e32 v0, v0, v2
	v_mov_b32_e32 v2, 0xfffffed8
	v_mov_b32_e32 v3, 0x78
	v_cmp_gt_u32_e32 vcc, 0x288, v0
	s_nop 1
	v_cndmask_b32_e32 v2, v2, v3, vcc
	v_mov_b32_e32 v3, 0x158
	v_cmp_gt_u32_e32 vcc, 0x1e8, v0
	s_nop 1
	v_cndmask_b32_e32 v2, v2, v3, vcc
	v_mov_b32_e32 v3, 0xffffffb8
	v_cmp_gt_u32_e32 vcc, 0x1a8, v0
	s_nop 1
	v_cndmask_b32_e32 v2, v2, v3, vcc
	v_mov_b32_e32 v3, 0x340
	v_cmp_gt_u32_e32 vcc, 0x48, v0
	s_nop 1
	v_cndmask_b32_e32 v2, v2, v3, vcc
	v_add_u32_e32 v0, v0, v2
	s_movk_i32 s18, 0x340
	v_cmp_gt_i32_e32 vcc, s18, v0
	s_and_saveexec_b64 s[38:39], vcc
	s_xor_b64 s[38:39], exec, s[38:39]
	v_writelane_b32 v250, s38, 35
	s_nop 1
	v_writelane_b32 v250, s39, 36
	s_cbranch_execz .LBB0_259
	s_movk_i32 s18, 0x260
	v_add_u32_e32 v2, 0xfffffea0, v0
	v_cmp_gt_i32_e32 vcc, s18, v0
	s_movk_i32 s18, 0x1a0
	s_mov_b64 s[42:43], 0
	v_cndmask_b32_e32 v3, v218, v219, vcc
	v_cmp_gt_u32_e32 vcc, s18, v2
	s_movk_i32 s18, 0x1ff
	s_nop 0
	v_cndmask_b32_e32 v2, 0, v3, vcc
	v_add_u32_e32 v2, v2, v0
	v_cmp_lt_i32_e64 s[38:39], s18, v2
	s_and_saveexec_b64 s[18:19], s[38:39]
	s_xor_b64 s[18:19], exec, s[18:19]
	s_cbranch_execz .LBB0_57
	s_and_saveexec_b64 s[24:25], s[44:45]
	s_cbranch_execz .LBB0_56
	s_and_saveexec_b64 s[42:43], s[36:37]
	s_cbranch_execz .LBB0_55
	v_readlane_b32 s44, v252, 2
	v_readlane_b32 s45, v252, 3
	s_load_dword s34, s[44:45], 0x10
	s_load_dword s46, s[44:45], 0x0
	s_waitcnt lgkmcnt(0)
	s_lshr_b32 s34, s34, 16
	s_cmp_lg_u32 s34, 0
	s_cselect_b64 s[44:45], -1, 0
	s_cmp_lg_u64 s[44:45], 0
	s_addc_u32 s34, s46, 0
	s_mov_b32 s46, 0x1000000
	s_branch .LBB0_44
